# attention softmax: the cross-lane max / sum reductions use v_permlane16_swap + v_permlane32_swap (VALU) instead of ds_bpermute round trips
# speedup vs baseline: 1.0059x; 1.0059x over previous
; __device__ __forceinline__ void nat_phase(const Params& p, float* ldsf, int wave0, int nwaves) {
;     ...
;         for (int qt = 0; qt < 4; ++qt) {
;             const int c0 = qt * 16, cs0 = (qt == 0) ? 0 : (qt == 1 ? 8 : (qt == 2 ? 24 : 32));
;             const int c = c0 + l15, csq = min(max(c - 8, 0), 48);
;             const bf16x8 bq0 = *(const bf16x8*)(Qb + (size_t)c * RW + lq * 8), bq1 = *(const bf16x8*)(Qb + (size_t)c * RW + 32 + lq * 8);
;             f32x4 sc[8][2];
; #pragma unroll
;             for (int i = 0; i < 8; ++i)
; #pragma unroll
;                 for (int hf = 0; hf < 2; ++hf) { const u16* kp = Kb + (size_t)(i * 64 + cs0 + (l15 >> 2) * 8 + hf * 4 + (l15 & 3)) * RW + lq * 8;
;                     const bf16x8 a0 = *(const bf16x8*)kp, a1 = *(const bf16x8*)(kp + 32); f32x4 z = {0.f, 0.f, 0.f, 0.f};
;                     z = __builtin_amdgcn_mfma_f32_16x16x32_bf16(a0, bq0, z, 0, 0, 0); z = __builtin_amdgcn_mfma_f32_16x16x32_bf16(a1, bq1, z, 0, 0, 0); sc[i][hf] = z; }
;             float mx = -1e30f;
; #pragma unroll
;             for (int i = 0; i < 8; ++i)
; #pragma unroll
;                 for (int hf = 0; hf < 2; ++hf)
; #pragma unroll
;                     for (int j = 0; j < 4; ++j) { const int kc = cs0 + lq * 8 + hf * 4 + j; const bool valid = (kc >= csq) && (kc < csq + 16); const int bc = valid ? (kc - c + 15) : 0;
;                         const float s = valid ? sc[i][hf][j] * 0.125f + tb[i * 31 + bc] : -1e30f; sc[i][hf][j] = s; mx = fmaxf(mx, s); }
;             mx = fmaxf(mx, __shfl_xor(mx, 16)); mx = fmaxf(mx, __shfl_xor(mx, 32));
.Lmy_nat_p2j:
	s_waitcnt lgkmcnt(0)
	ds_read_b128 v[0:3], v32 offset:0
	ds_read_b128 v[4:7], v32 offset:1024
	ds_read_b128 v[8:11], v32 offset:2048
	ds_read_b128 v[12:15], v32 offset:3072
	ds_read_b128 v[16:19], v32 offset:4096
	ds_read_b128 v[20:23], v32 offset:5120
	ds_read_b128 v[24:27], v32 offset:6144
	ds_read_b128 v[28:31], v32 offset:7168
	s_waitcnt lgkmcnt(7)
	v_mfma_f32_16x16x32_bf16 v[128:131], v[0:3], v[192:195], v[128:131]
	ds_read_b128 v[0:3], v32 offset:8192
	s_waitcnt lgkmcnt(7)
	v_mfma_f32_16x16x32_bf16 v[128:131], v[4:7], v[196:199], v[128:131]
	ds_read_b128 v[4:7], v32 offset:9216
	s_waitcnt lgkmcnt(7)
	v_mfma_f32_16x16x32_bf16 v[132:135], v[8:11], v[192:195], v[132:135]
	ds_read_b128 v[8:11], v32 offset:10240
	s_waitcnt lgkmcnt(7)
	v_mfma_f32_16x16x32_bf16 v[132:135], v[12:15], v[196:199], v[132:135]
	ds_read_b128 v[12:15], v32 offset:11264
	s_waitcnt lgkmcnt(7)
	v_mfma_f32_16x16x32_bf16 v[136:139], v[16:19], v[192:195], v[136:139]
	ds_read_b128 v[16:19], v32 offset:12288
	s_waitcnt lgkmcnt(7)
	v_mfma_f32_16x16x32_bf16 v[136:139], v[20:23], v[196:199], v[136:139]
	ds_read_b128 v[20:23], v32 offset:13312
	s_waitcnt lgkmcnt(7)
	v_mfma_f32_16x16x32_bf16 v[140:143], v[24:27], v[192:195], v[140:143]
	ds_read_b128 v[24:27], v32 offset:14336
	s_waitcnt lgkmcnt(7)
	v_mfma_f32_16x16x32_bf16 v[140:143], v[28:31], v[196:199], v[140:143]
	ds_read_b128 v[28:31], v32 offset:15360
	s_waitcnt lgkmcnt(7)
	v_mfma_f32_16x16x32_bf16 v[144:147], v[0:3], v[192:195], v[144:147]
	ds_read_b128 v[0:3], v32 offset:16384
	s_waitcnt lgkmcnt(7)
	v_mfma_f32_16x16x32_bf16 v[144:147], v[4:7], v[196:199], v[144:147]
	ds_read_b128 v[4:7], v32 offset:17408
	s_waitcnt lgkmcnt(7)
	v_mfma_f32_16x16x32_bf16 v[148:151], v[8:11], v[192:195], v[148:151]
	ds_read_b128 v[8:11], v32 offset:18432
	s_waitcnt lgkmcnt(7)
	v_mfma_f32_16x16x32_bf16 v[148:151], v[12:15], v[196:199], v[148:151]
	ds_read_b128 v[12:15], v32 offset:19456
	s_waitcnt lgkmcnt(7)
	v_mfma_f32_16x16x32_bf16 v[152:155], v[16:19], v[192:195], v[152:155]
	ds_read_b128 v[16:19], v32 offset:20480
	s_waitcnt lgkmcnt(7)
	v_mfma_f32_16x16x32_bf16 v[152:155], v[20:23], v[196:199], v[152:155]
	ds_read_b128 v[20:23], v32 offset:21504
	s_waitcnt lgkmcnt(7)
	v_mfma_f32_16x16x32_bf16 v[156:159], v[24:27], v[192:195], v[156:159]
	ds_read_b128 v[24:27], v32 offset:22528
	s_waitcnt lgkmcnt(7)
	v_mfma_f32_16x16x32_bf16 v[156:159], v[28:31], v[196:199], v[156:159]
	ds_read_b128 v[28:31], v32 offset:23552
	s_waitcnt lgkmcnt(7)
	v_mfma_f32_16x16x32_bf16 v[160:163], v[0:3], v[192:195], v[160:163]
	ds_read_b128 v[0:3], v32 offset:24576
	s_waitcnt lgkmcnt(7)
	v_mfma_f32_16x16x32_bf16 v[160:163], v[4:7], v[196:199], v[160:163]
	ds_read_b128 v[4:7], v32 offset:25600
	s_waitcnt lgkmcnt(7)
	v_mfma_f32_16x16x32_bf16 v[164:167], v[8:11], v[192:195], v[164:167]
	ds_read_b128 v[8:11], v32 offset:26624
	s_waitcnt lgkmcnt(7)
	v_mfma_f32_16x16x32_bf16 v[164:167], v[12:15], v[196:199], v[164:167]
	ds_read_b128 v[12:15], v32 offset:27648
	s_waitcnt lgkmcnt(7)
	v_mfma_f32_16x16x32_bf16 v[168:171], v[16:19], v[192:195], v[168:171]
	ds_read_b128 v[16:19], v32 offset:28672
	s_waitcnt lgkmcnt(7)
	v_mfma_f32_16x16x32_bf16 v[168:171], v[20:23], v[196:199], v[168:171]
	ds_read_b128 v[20:23], v32 offset:29696
	s_waitcnt lgkmcnt(7)
	v_mfma_f32_16x16x32_bf16 v[172:175], v[24:27], v[192:195], v[172:175]
	ds_read_b128 v[24:27], v32 offset:30720
	s_waitcnt lgkmcnt(7)
	v_mfma_f32_16x16x32_bf16 v[172:175], v[28:31], v[196:199], v[172:175]
	ds_read_b128 v[28:31], v32 offset:31744
	s_waitcnt lgkmcnt(7)
	v_mfma_f32_16x16x32_bf16 v[176:179], v[0:3], v[192:195], v[176:179]
	s_waitcnt lgkmcnt(6)
	v_mfma_f32_16x16x32_bf16 v[176:179], v[4:7], v[196:199], v[176:179]
	s_waitcnt lgkmcnt(5)
	v_mfma_f32_16x16x32_bf16 v[180:183], v[8:11], v[192:195], v[180:183]
	s_waitcnt lgkmcnt(4)
	v_mfma_f32_16x16x32_bf16 v[180:183], v[12:15], v[196:199], v[180:183]
	s_waitcnt lgkmcnt(3)
	v_mfma_f32_16x16x32_bf16 v[184:187], v[16:19], v[192:195], v[184:187]
	s_waitcnt lgkmcnt(2)
	v_mfma_f32_16x16x32_bf16 v[184:187], v[20:23], v[196:199], v[184:187]
	s_waitcnt lgkmcnt(1)
	v_mfma_f32_16x16x32_bf16 v[188:191], v[24:27], v[192:195], v[188:191]
	s_waitcnt lgkmcnt(0)
	v_mfma_f32_16x16x32_bf16 v[188:191], v[28:31], v[196:199], v[188:191]
	s_lshl_b32 s84, s82, 11
	s_add_u32 s84, s84, s79
	buffer_load_dwordx2 v[216:217], v227, s[68:71], s84 offen offset:0
	buffer_load_dwordx2 v[218:219], v227, s[68:71], s84 offen offset:32
	buffer_load_dwordx2 v[220:221], v227, s[68:71], s84 offen offset:64
	buffer_load_dwordx2 v[222:223], v227, s[68:71], s84 offen offset:96
	v_max3_f32 v239, v128, v129, v130
	v_max3_f32 v239, v239, v131, v132
	v_max3_f32 v239, v239, v133, v134
	v_max3_f32 v239, v239, v135, v136
	v_max3_f32 v239, v239, v137, v138
	v_max3_f32 v239, v239, v139, v140
	v_max3_f32 v239, v239, v141, v142
	v_max3_f32 v239, v239, v143, v144
	v_max3_f32 v239, v239, v145, v146
	v_max3_f32 v239, v239, v147, v148
	v_max3_f32 v239, v239, v149, v150
	v_max3_f32 v239, v239, v151, v152
	v_max3_f32 v239, v239, v153, v154
	v_max3_f32 v239, v239, v155, v156
	v_max3_f32 v239, v239, v157, v158
	v_max3_f32 v239, v239, v159, v160
	v_max3_f32 v239, v239, v161, v162
	v_max3_f32 v239, v239, v163, v164
	v_max3_f32 v239, v239, v165, v166
	v_max3_f32 v239, v239, v167, v168
	v_max3_f32 v239, v239, v169, v170
	v_max3_f32 v239, v239, v171, v172
	v_max3_f32 v239, v239, v173, v174
	v_max3_f32 v239, v239, v175, v176
	v_max3_f32 v239, v239, v177, v178
	v_max3_f32 v239, v239, v179, v180
	v_max3_f32 v239, v239, v181, v182
	v_max3_f32 v239, v239, v183, v184
	v_max3_f32 v239, v239, v185, v186
	v_max3_f32 v239, v239, v187, v188
; __device__ __forceinline__ void nat_phase(const Params& p, float* ldsf, int wave0, int nwaves) {
;     ...
;             mx = fmaxf(mx, __shfl_xor(mx, 16)); mx = fmaxf(mx, __shfl_xor(mx, 32));
;             float sum = 0.f;
; #pragma unroll
;             for (int i = 0; i < 8; ++i)
; #pragma unroll
;                 for (int hf = 0; hf < 2; ++hf)
; #pragma unroll
;                     for (int j = 0; j < 4; ++j) { const float e = __expf(sc[i][hf][j] - mx); sc[i][hf][j] = e; sum += e; }
	v_max3_f32 v239, v239, v189, v190
	v_max_f32_e32 v239, v239, v191
	v_mov_b32_e32 v242, v239
	s_nop 1
	v_permlane16_swap_b32 v242, v239
	v_max_f32_e32 v239, v239, v242
	v_mov_b32_e32 v242, v239
	s_nop 1
	v_permlane32_swap_b32 v242, v239
	v_max_f32_e32 v239, v239, v242
	v_mul_f32_e64 v242, -v239, v252
	v_mov_b32_e32 v243, v242
	v_pk_fma_f32 v[128:129], v[128:129], v[252:253], v[242:243]
	v_pk_fma_f32 v[130:131], v[130:131], v[252:253], v[242:243]
	v_pk_fma_f32 v[132:133], v[132:133], v[252:253], v[242:243]
	v_pk_fma_f32 v[134:135], v[134:135], v[252:253], v[242:243]
	v_pk_fma_f32 v[136:137], v[136:137], v[252:253], v[242:243]
	v_pk_fma_f32 v[138:139], v[138:139], v[252:253], v[242:243]
	v_pk_fma_f32 v[140:141], v[140:141], v[252:253], v[242:243]
	v_pk_fma_f32 v[142:143], v[142:143], v[252:253], v[242:243]
	v_pk_fma_f32 v[144:145], v[144:145], v[252:253], v[242:243]
	v_pk_fma_f32 v[146:147], v[146:147], v[252:253], v[242:243]
	v_pk_fma_f32 v[148:149], v[148:149], v[252:253], v[242:243]
	v_pk_fma_f32 v[150:151], v[150:151], v[252:253], v[242:243]
	v_pk_fma_f32 v[152:153], v[152:153], v[252:253], v[242:243]
	v_pk_fma_f32 v[154:155], v[154:155], v[252:253], v[242:243]
	v_pk_fma_f32 v[156:157], v[156:157], v[252:253], v[242:243]
	v_pk_fma_f32 v[158:159], v[158:159], v[252:253], v[242:243]
	v_pk_fma_f32 v[160:161], v[160:161], v[252:253], v[242:243]
	v_pk_fma_f32 v[162:163], v[162:163], v[252:253], v[242:243]
	v_pk_fma_f32 v[164:165], v[164:165], v[252:253], v[242:243]
	v_pk_fma_f32 v[166:167], v[166:167], v[252:253], v[242:243]
	v_pk_fma_f32 v[168:169], v[168:169], v[252:253], v[242:243]
	v_pk_fma_f32 v[170:171], v[170:171], v[252:253], v[242:243]
	v_pk_fma_f32 v[172:173], v[172:173], v[252:253], v[242:243]
	v_pk_fma_f32 v[174:175], v[174:175], v[252:253], v[242:243]
	v_pk_fma_f32 v[176:177], v[176:177], v[252:253], v[242:243]
	v_pk_fma_f32 v[178:179], v[178:179], v[252:253], v[242:243]
	v_pk_fma_f32 v[180:181], v[180:181], v[252:253], v[242:243]
	v_pk_fma_f32 v[182:183], v[182:183], v[252:253], v[242:243]
	v_pk_fma_f32 v[184:185], v[184:185], v[252:253], v[242:243]
	v_pk_fma_f32 v[186:187], v[186:187], v[252:253], v[242:243]
	v_pk_fma_f32 v[188:189], v[188:189], v[252:253], v[242:243]
	v_pk_fma_f32 v[190:191], v[190:191], v[252:253], v[242:243]
	v_exp_f32_e32 v128, v128
	v_exp_f32_e32 v129, v129
	v_exp_f32_e32 v130, v130
	v_exp_f32_e32 v131, v131
	v_exp_f32_e32 v132, v132
	v_exp_f32_e32 v133, v133
	v_exp_f32_e32 v134, v134
	v_exp_f32_e32 v135, v135
	v_exp_f32_e32 v136, v136
	v_exp_f32_e32 v137, v137
	v_exp_f32_e32 v138, v138
	v_exp_f32_e32 v139, v139
	v_exp_f32_e32 v140, v140
	v_exp_f32_e32 v141, v141
	v_exp_f32_e32 v142, v142
	v_exp_f32_e32 v143, v143
	v_exp_f32_e32 v144, v144
	v_exp_f32_e32 v145, v145
	v_exp_f32_e32 v146, v146
	v_exp_f32_e32 v147, v147
	v_exp_f32_e32 v148, v148
	v_exp_f32_e32 v149, v149
	v_exp_f32_e32 v150, v150
	v_exp_f32_e32 v151, v151
	v_exp_f32_e32 v152, v152
	v_exp_f32_e32 v153, v153
	v_exp_f32_e32 v154, v154
	v_exp_f32_e32 v155, v155
	v_exp_f32_e32 v156, v156
	v_exp_f32_e32 v157, v157
	v_exp_f32_e32 v158, v158
	v_exp_f32_e32 v159, v159
	v_exp_f32_e32 v160, v160
	v_exp_f32_e32 v161, v161
	v_exp_f32_e32 v162, v162
	v_exp_f32_e32 v163, v163
	v_exp_f32_e32 v164, v164
	v_exp_f32_e32 v165, v165
	v_exp_f32_e32 v166, v166
	v_exp_f32_e32 v167, v167
	v_exp_f32_e32 v168, v168
	v_exp_f32_e32 v169, v169
	v_exp_f32_e32 v170, v170
	v_exp_f32_e32 v171, v171
	v_exp_f32_e32 v172, v172
	v_exp_f32_e32 v173, v173
	v_exp_f32_e32 v174, v174
	v_exp_f32_e32 v175, v175
	v_exp_f32_e32 v176, v176
	v_exp_f32_e32 v177, v177
	v_exp_f32_e32 v178, v178
	v_exp_f32_e32 v179, v179
	v_exp_f32_e32 v180, v180
	v_exp_f32_e32 v181, v181
	v_exp_f32_e32 v182, v182
	v_exp_f32_e32 v183, v183
	v_exp_f32_e32 v184, v184
	v_exp_f32_e32 v185, v185
	v_exp_f32_e32 v186, v186
	v_exp_f32_e32 v187, v187
	v_exp_f32_e32 v188, v188
	v_exp_f32_e32 v189, v189
	v_exp_f32_e32 v190, v190
	v_exp_f32_e32 v191, v191
	s_nop 0
	v_pk_add_f32 v[244:245], v[128:129], v[130:131]
	v_pk_add_f32 v[246:247], v[132:133], v[134:135]
	v_pk_add_f32 v[244:245], v[244:245], v[136:137]
	v_pk_add_f32 v[246:247], v[246:247], v[138:139]
	v_pk_add_f32 v[244:245], v[244:245], v[140:141]
	v_pk_add_f32 v[246:247], v[246:247], v[142:143]
	v_pk_add_f32 v[244:245], v[244:245], v[144:145]
; __device__ __forceinline__ unsigned cvt_pk_bf16(float lo, float hi) { unsigned r; asm volatile("v_cvt_pk_bf16_f32 %0, %1, %2" : "=v"(r) : "v"(lo), "v"(hi)); return r; }
; __device__ __forceinline__ void nat_phase(const Params& p, float* ldsf, int wave0, int nwaves) {
;     ...
;                     for (int j = 0; j < 4; ++j) { const float e = __expf(sc[i][hf][j] - mx); sc[i][hf][j] = e; sum += e; }
;             sum += __shfl_xor(sum, 16); sum += __shfl_xor(sum, 32);
;             const float inv = 1.0f / sum;
;             f32x4 o[4];
; #pragma unroll
;             for (int mt = 0; mt < 4; ++mt) o[mt] = (f32x4){0.f, 0.f, 0.f, 0.f};
; #pragma unroll
;             for (int i = 0; i < 8; ++i) {
;                 u32x4 pw; pw.x = cvt_pk_bf16(sc[i][0][0] * inv, sc[i][0][1] * inv); pw.y = cvt_pk_bf16(sc[i][0][2] * inv, sc[i][0][3] * inv);
;                 pw.z = cvt_pk_bf16(sc[i][1][0] * inv, sc[i][1][1] * inv); pw.w = cvt_pk_bf16(sc[i][1][2] * inv, sc[i][1][3] * inv);
;                 const bf16x8 bp = __builtin_bit_cast(bf16x8, pw);
	v_pk_add_f32 v[246:247], v[246:247], v[146:147]
	v_pk_add_f32 v[244:245], v[244:245], v[148:149]
	v_pk_add_f32 v[246:247], v[246:247], v[150:151]
	v_pk_add_f32 v[244:245], v[244:245], v[152:153]
	v_pk_add_f32 v[246:247], v[246:247], v[154:155]
	v_pk_add_f32 v[244:245], v[244:245], v[156:157]
	v_pk_add_f32 v[246:247], v[246:247], v[158:159]
	v_pk_add_f32 v[244:245], v[244:245], v[160:161]
	v_pk_add_f32 v[246:247], v[246:247], v[162:163]
	v_pk_add_f32 v[244:245], v[244:245], v[164:165]
	v_pk_add_f32 v[246:247], v[246:247], v[166:167]
	v_pk_add_f32 v[244:245], v[244:245], v[168:169]
	v_pk_add_f32 v[246:247], v[246:247], v[170:171]
	v_pk_add_f32 v[244:245], v[244:245], v[172:173]
	v_pk_add_f32 v[246:247], v[246:247], v[174:175]
	v_pk_add_f32 v[244:245], v[244:245], v[176:177]
	v_pk_add_f32 v[246:247], v[246:247], v[178:179]
	v_pk_add_f32 v[244:245], v[244:245], v[180:181]
	v_pk_add_f32 v[246:247], v[246:247], v[182:183]
	v_pk_add_f32 v[244:245], v[244:245], v[184:185]
	v_pk_add_f32 v[246:247], v[246:247], v[186:187]
	v_pk_add_f32 v[244:245], v[244:245], v[188:189]
	v_pk_add_f32 v[246:247], v[246:247], v[190:191]
	v_pk_add_f32 v[244:245], v[244:245], v[246:247]
	v_add_f32_e32 v240, v244, v245
	v_mov_b32_e32 v242, v240
	s_nop 1
	v_permlane16_swap_b32 v242, v240
	v_add_f32_e32 v240, v240, v242
	v_mov_b32_e32 v242, v240
	s_nop 1
	v_permlane32_swap_b32 v242, v240
	v_add_f32_e32 v240, v240, v242
	v_rcp_f32_e32 v242, v240
	s_nop 0
	v_mov_b32_e32 v243, v242
	v_pk_mul_f32 v[128:129], v[128:129], v[242:243]
	v_pk_mul_f32 v[130:131], v[130:131], v[242:243]
	v_pk_mul_f32 v[132:133], v[132:133], v[242:243]
	v_pk_mul_f32 v[134:135], v[134:135], v[242:243]
	v_pk_mul_f32 v[136:137], v[136:137], v[242:243]
	v_pk_mul_f32 v[138:139], v[138:139], v[242:243]
	v_pk_mul_f32 v[140:141], v[140:141], v[242:243]
	v_pk_mul_f32 v[142:143], v[142:143], v[242:243]
	v_pk_mul_f32 v[144:145], v[144:145], v[242:243]
	v_pk_mul_f32 v[146:147], v[146:147], v[242:243]
	v_pk_mul_f32 v[148:149], v[148:149], v[242:243]
	v_pk_mul_f32 v[150:151], v[150:151], v[242:243]
	v_pk_mul_f32 v[152:153], v[152:153], v[242:243]
	v_pk_mul_f32 v[154:155], v[154:155], v[242:243]
	v_pk_mul_f32 v[156:157], v[156:157], v[242:243]
	v_pk_mul_f32 v[158:159], v[158:159], v[242:243]
	v_pk_mul_f32 v[160:161], v[160:161], v[242:243]
	v_pk_mul_f32 v[162:163], v[162:163], v[242:243]
	v_pk_mul_f32 v[164:165], v[164:165], v[242:243]
	v_pk_mul_f32 v[166:167], v[166:167], v[242:243]
	v_pk_mul_f32 v[168:169], v[168:169], v[242:243]
	v_pk_mul_f32 v[170:171], v[170:171], v[242:243]
	v_pk_mul_f32 v[172:173], v[172:173], v[242:243]
	v_pk_mul_f32 v[174:175], v[174:175], v[242:243]
	v_pk_mul_f32 v[176:177], v[176:177], v[242:243]
	v_pk_mul_f32 v[178:179], v[178:179], v[242:243]
	v_pk_mul_f32 v[180:181], v[180:181], v[242:243]
	v_pk_mul_f32 v[182:183], v[182:183], v[242:243]
	v_pk_mul_f32 v[184:185], v[184:185], v[242:243]
	v_pk_mul_f32 v[186:187], v[186:187], v[242:243]
	v_pk_mul_f32 v[188:189], v[188:189], v[242:243]
	v_pk_mul_f32 v[190:191], v[190:191], v[242:243]
	v_cvt_pk_bf16_f32 v128, v128, v129
	v_cvt_pk_bf16_f32 v129, v130, v131
	v_cvt_pk_bf16_f32 v130, v132, v133
	v_cvt_pk_bf16_f32 v131, v134, v135
	v_cvt_pk_bf16_f32 v136, v136, v137
	v_cvt_pk_bf16_f32 v137, v138, v139
	v_cvt_pk_bf16_f32 v138, v140, v141
	v_cvt_pk_bf16_f32 v139, v142, v143
	v_cvt_pk_bf16_f32 v144, v144, v145
	v_cvt_pk_bf16_f32 v145, v146, v147
	v_cvt_pk_bf16_f32 v146, v148, v149
	v_cvt_pk_bf16_f32 v147, v150, v151
	v_cvt_pk_bf16_f32 v152, v152, v153
	v_cvt_pk_bf16_f32 v153, v154, v155
	v_cvt_pk_bf16_f32 v154, v156, v157
	v_cvt_pk_bf16_f32 v155, v158, v159
	v_cvt_pk_bf16_f32 v160, v160, v161
	v_cvt_pk_bf16_f32 v161, v162, v163
	v_cvt_pk_bf16_f32 v162, v164, v165
	v_cvt_pk_bf16_f32 v163, v166, v167
	v_cvt_pk_bf16_f32 v168, v168, v169
	v_cvt_pk_bf16_f32 v169, v170, v171
	v_cvt_pk_bf16_f32 v170, v172, v173
	v_cvt_pk_bf16_f32 v171, v174, v175
	v_cvt_pk_bf16_f32 v176, v176, v177
	v_cvt_pk_bf16_f32 v177, v178, v179
	v_cvt_pk_bf16_f32 v178, v180, v181
	v_cvt_pk_bf16_f32 v179, v182, v183
	v_cvt_pk_bf16_f32 v184, v184, v185
	v_cvt_pk_bf16_f32 v185, v186, v187
	v_cvt_pk_bf16_f32 v186, v188, v189
	v_cvt_pk_bf16_f32 v187, v190, v191
	s_cmp_lt_u32 s1, 4
	s_cbranch_scc1 .Lmy_nat_p3j
	s_waitcnt vmcnt(4)
